# combine phase: U-row loads issued together with the O loads at the top of each row (one round trip per row instead of three)
# speedup vs baseline: 1.0678x; 1.0064x over previous
; __device__ __forceinline__ unsigned pk2(float lo, float hi) { return f2bf(lo) | (f2bf(hi) << 16); }
; __global__ void __launch_bounds__(NWAVES * 64, 2) hymba_fwd(Args args) {
;     ...
;                 for (int mc = mc0; mc < M / 8; mc += mcs) { float wsum[8];
;                   for (int mr = 0; mr < 8; ++mr) { const int m = mc * 8 + mr;
;                     const v4u a = *(const v4u*)(OBUF + (size_t)m * 1024 + hd * 256 + j0), b = *(const v4u*)(OBUF + (size_t)m * 1024 + hd * 256 + 128 + j0);
;                     float o[8];
;                     o[0] = bflo(a.x) - lam * bflo(b.x); o[1] = bfhi(a.x) - lam * bfhi(b.x); o[2] = bflo(a.y) - lam * bflo(b.y); o[3] = bfhi(a.y) - lam * bfhi(b.y);
;                     o[4] = bflo(a.z) - lam * bflo(b.z); o[5] = bfhi(a.z) - lam * bfhi(b.z); o[6] = bflo(a.w) - lam * bflo(b.w); o[7] = bfhi(a.w) - lam * bfhi(b.w);
;                     float ss = 0.f;
; #pragma unroll
;                     for (int j = 0; j < 8; ++j) ss += o[j] * o[j];
;                     ss += __shfl_xor(ss, 1); ss += __shfl_xor(ss, 2); ss += __shfl_xor(ss, 4); ss += __shfl_xor(ss, 8);
;                     const float rr = __builtin_amdgcn_rsqf(ss * (1.0f / 128.0f) + 1e-6f);
;                     v4u w; w.x = pk2(o[0] * rr * gn[0], o[1] * rr * gn[1]); w.y = pk2(o[2] * rr * gn[2], o[3] * rr * gn[3]); w.z = pk2(o[4] * rr * gn[4], o[5] * rr * gn[5]); w.w = pk2(o[6] * rr * gn[6], o[7] * rr * gn[7]);
;                     *(v4u*)(CAT + (size_t)m * 1024 + hd * 128 + j0) = w;
;                     const bf16* up = QKVU + (size_t)m * 2112 + 1536 + hd * 128 + j0;
;                     const v4u u0 = *(const v4u*)up;
;                     const float us[8] = {bflo(u0.x), bfhi(u0.x), bflo(u0.y), bfhi(u0.y), bflo(u0.z), bfhi(u0.z), bflo(u0.w), bfhi(u0.w)};
;                     float sm[8];
;                     if (mr == 0) {
;                         v4u ut[15]; float wt[15];
; #pragma unroll
;                         for (int j = 0; j < 8; ++j) sm[j] = us[j];
; #pragma unroll
;                         for (int t = 1; t < 16; ++t) { const bool ok = (t < win) && (m - t >= 0); ut[t - 1] = *(const v4u*)(up - (size_t)(ok ? t : 0) * 2112); wt[t - 1] = ok ? 1.0f : 0.0f; }
; #pragma unroll
;                         for (int t = 0; t < 15; ++t) { const float w = wt[t];
.LBB0_438:
	s_add_i32 s86, s0, s41
	s_mov_b64 s[42:43], s[38:39]
	s_ashr_i32 s87, s86, 31
	s_lshl_b64 s[64:65], s[86:87], 11
	s_add_u32 s42, s42, s64
	s_addc_u32 s43, s43, s65
	v_lshl_add_u64 v[0:1], s[42:43], 0, v[42:43]
	v_lshlrev_b32_e32 v160, 1, v30
	v_lshl_add_u64 v[0:1], v[0:1], 0, v[160:161]
	v_add_co_u32_e32 v0, vcc, s96, v0
	s_mov_b64 s[42:43], s[38:39]
	s_nop 0
	v_addc_co_u32_e32 v1, vcc, 0, v1, vcc
	global_load_dwordx4 v[0:3], v[0:1], off
	s_add_u32 s42, s42, s64
	s_addc_u32 s43, s43, s65
	v_lshl_add_u64 v[4:5], s[42:43], 0, v[42:43]
	v_lshl_add_u64 v[4:5], v[4:5], 0, v[160:161]
	v_add_co_u32_e32 v4, vcc, s96, v4
	s_mov_b64 s[42:43], s[38:39]
	s_nop 0
	v_addc_co_u32_e32 v5, vcc, 0, v5, vcc
	global_load_dwordx4 v[4:7], v[4:5], off offset:256
	s_add_u32 s42, s42, s64
	s_addc_u32 s43, s43, s65
	s_mul_i32 s45, s86, 0x1080
	s_mul_hi_i32 s44, s86, 0x1080
	s_add_u32 s100, s38, s45
	s_addc_u32 s101, s39, s44
	v_cmp_lt_i32_e32 vcc, s86, v59
	v_lshlrev_b64 v[236:237], 1, v[40:41]
	v_lshl_add_u64 v[236:237], s[100:101], 0, v[236:237]
	v_lshl_add_u64 v[236:237], v[236:237], 0, v[160:161]
	s_mov_b64 s[100:101], 0x2800c00
	v_cndmask_b32_e64 v240, v59, 0, vcc
	v_lshl_add_u64 v[236:237], v[236:237], 0, s[100:101]
	v_mul_i32_i24_e32 v240, 0xffffef80, v240
	v_ashrrev_i32_e32 v241, 31, v240
	v_lshl_add_u64 v[240:241], v[236:237], 0, v[240:241]
	global_load_dwordx4 v[236:239], v[236:237], off
	global_load_dwordx4 v[240:243], v[240:241], off
	s_waitcnt vmcnt(3)
	v_lshlrev_b32_e32 v9, 16, v1
	v_lshlrev_b32_e32 v8, 16, v0
	v_and_b32_e32 v1, 0xffff0000, v1
	v_and_b32_e32 v0, 0xffff0000, v0
	v_lshlrev_b32_e32 v13, 16, v3
	v_lshlrev_b32_e32 v12, 16, v2
	v_and_b32_e32 v3, 0xffff0000, v3
	v_and_b32_e32 v2, 0xffff0000, v2
	s_waitcnt vmcnt(2)
	v_lshlrev_b32_e32 v11, 16, v5
	v_lshlrev_b32_e32 v10, 16, v4
	v_and_b32_e32 v5, 0xffff0000, v5
	v_and_b32_e32 v4, 0xffff0000, v4
	v_pk_fma_f32 v[8:9], v[28:29], v[10:11], v[8:9] neg_lo:[1,0,0] neg_hi:[1,0,0]
	v_pk_fma_f32 v[0:1], v[28:29], v[4:5], v[0:1] neg_lo:[1,0,0] neg_hi:[1,0,0]
	v_pk_mul_f32 v[4:5], v[8:9], v[8:9]
	v_pk_mul_f32 v[10:11], v[0:1], v[0:1]
	v_lshlrev_b32_e32 v15, 16, v7
	v_lshlrev_b32_e32 v14, 16, v6
	v_and_b32_e32 v7, 0xffff0000, v7
	v_and_b32_e32 v6, 0xffff0000, v6
	v_pk_fma_f32 v[12:13], v[28:29], v[14:15], v[12:13] neg_lo:[1,0,0] neg_hi:[1,0,0]
	v_pk_fma_f32 v[2:3], v[28:29], v[6:7], v[2:3] neg_lo:[1,0,0] neg_hi:[1,0,0]
	v_add_f32_e32 v4, v4, v10
	v_mov_b32_e32 v6, v12
	v_mov_b32_e32 v7, v2
	v_add_f32_e32 v4, v4, v5
	v_pk_mul_f32 v[6:7], v[6:7], v[6:7]
	v_add_f32_e32 v4, v4, v11
	v_mov_b32_e32 v14, v13
	v_mov_b32_e32 v15, v3
	v_add_f32_e32 v4, v4, v6
	v_pk_mul_f32 v[14:15], v[14:15], v[14:15]
	v_add_f32_e32 v4, v4, v7
	v_add_f32_e32 v4, v4, v14
	v_add_f32_e32 v4, v4, v15
	ds_bpermute_b32 v5, v31, v4
	s_waitcnt lgkmcnt(0)
	v_add_f32_e32 v4, v4, v5
	ds_bpermute_b32 v5, v53, v4
	s_waitcnt lgkmcnt(0)
	v_add_f32_e32 v4, v4, v5
	ds_bpermute_b32 v5, v55, v4
	s_waitcnt lgkmcnt(0)
	v_add_f32_e32 v4, v4, v5
	ds_bpermute_b32 v5, v57, v4
	s_waitcnt lgkmcnt(0)
	v_add_f32_e32 v4, v4, v5
	v_fmamk_f32 v4, v4, 0x3c000000, v225
	v_rsq_f32_e32 v4, v4
	s_nop 0
	v_pk_mul_f32 v[2:3], v[2:3], v[4:5] op_sel_hi:[1,0]
	v_pk_mul_f32 v[6:7], v[8:9], v[4:5] op_sel_hi:[1,0]
	v_pk_mul_f32 v[0:1], v[0:1], v[4:5] op_sel_hi:[1,0]
	v_pk_mul_f32 v[2:3], v[2:3], v[38:39]
	v_pk_mul_f32 v[6:7], v[32:33], v[6:7]
	v_pk_mul_f32 v[0:1], v[34:35], v[0:1]
	v_pk_mul_f32 v[8:9], v[12:13], v[4:5] op_sel_hi:[1,0]
	v_bfe_u32 v4, v3, 16, 1
	v_bfe_u32 v5, v2, 16, 1
	v_pk_mul_f32 v[8:9], v[8:9], v[36:37]
	v_bfe_u32 v10, v1, 16, 1
	v_bfe_u32 v11, v0, 16, 1
	v_add3_u32 v2, v2, v5, s97
	v_add3_u32 v3, v3, v4, s97
	v_bfe_u32 v4, v6, 16, 1
	v_bfe_u32 v5, v7, 16, 1
	v_add3_u32 v0, v0, v11, s97
	v_add3_u32 v1, v1, v10, s97
	v_bfe_u32 v10, v8, 16, 1
	v_bfe_u32 v11, v9, 16, 1
	v_add3_u32 v5, v7, v5, s97
	v_add3_u32 v4, v6, v4, s97
	v_add3_u32 v9, v9, v11, s97
	v_add3_u32 v8, v8, v10, s97
	v_lshrrev_b32_e32 v4, 16, v4
	v_lshrrev_b32_e32 v5, 16, v5
	v_lshrrev_b32_e32 v6, 16, v8
	v_lshrrev_b32_e32 v7, 16, v9
	v_and_or_b32 v1, v1, s94, v5
	v_and_or_b32 v0, v0, s94, v4
	v_lshlrev_b64 v[4:5], 1, v[40:41]
	v_and_or_b32 v3, v3, s94, v7
	v_and_or_b32 v2, v2, s94, v6
	v_lshl_add_u64 v[6:7], s[42:43], 0, v[4:5]
	v_lshl_add_u64 v[6:7], v[6:7], 0, v[160:161]
	s_mov_b32 s42, 0x8c00000
	v_add_co_u32_e32 v6, vcc, s42, v6
	s_mov_b64 s[42:43], s[38:39]
	s_nop 0
	v_addc_co_u32_e32 v7, vcc, 0, v7, vcc
	global_store_dwordx4 v[6:7], v[0:3], off
	s_add_u32 s42, s42, s45
	s_addc_u32 s43, s43, s44
	v_lshl_add_u64 v[0:1], s[42:43], 0, v[4:5]
	v_lshl_add_u64 v[0:1], v[0:1], 0, v[160:161]
	s_mov_b64 s[42:43], 0x2800c00
	v_lshl_add_u64 v[24:25], v[0:1], 0, s[42:43]
	s_mov_b32 s42, 0x2800000
	v_add_co_u32_e32 v0, vcc, s42, v0
	s_cmp_lg_u32 s41, 0
	s_nop 0
	v_addc_co_u32_e32 v1, vcc, 0, v1, vcc
	s_waitcnt vmcnt(2)
	v_lshlrev_b32_e32 v51, 16, v237
	v_lshlrev_b32_e32 v50, 16, v236
	v_and_b32_e32 v49, 0xffff0000, v237
	v_and_b32_e32 v48, 0xffff0000, v236
	v_lshlrev_b32_e32 v47, 16, v239
	v_lshlrev_b32_e32 v46, 16, v238
	v_and_b32_e32 v45, 0xffff0000, v239
	v_and_b32_e32 v44, 0xffff0000, v238
	s_cbranch_scc0 .LBB0_440
	v_cmp_lt_i32_e32 vcc, s86, v59
	s_movk_i32 s42, 0xef80
	v_mov_b32_e32 v4, v169
	v_cndmask_b32_e64 v0, v59, 0, vcc
	v_mad_i64_i32 v[0:1], s[42:43], v0, s42, v[24:25]
	v_mov_b32_e32 v169, v172
	v_mov_b32_e32 v8, v50
	v_mov_b32_e32 v9, v48
	v_cndmask_b32_e64 v6, 1.0, 0, vcc
	v_pk_add_f32 v[8:9], v[168:169], v[8:9]
	v_mov_b32_e32 v5, v173
	v_mov_b32_e32 v171, v174
	s_waitcnt vmcnt(1)
	v_lshlrev_b32_e32 v10, 16, v240
	v_and_b32_e32 v11, 0xffff0000, v240
	v_pk_fma_f32 v[8:9], v[6:7], v[10:11], v[8:9] op_sel_hi:[0,1,1] neg_lo:[1,0,0] neg_hi:[1,0,0]
	v_mov_b32_e32 v10, v51
	v_mov_b32_e32 v11, v49
	v_pk_add_f32 v[4:5], v[4:5], v[10:11]
	v_lshlrev_b32_e32 v0, 16, v241
	v_and_b32_e32 v1, 0xffff0000, v241
	v_pk_fma_f32 v[172:173], v[6:7], v[0:1], v[4:5] op_sel_hi:[0,1,1] neg_lo:[1,0,0] neg_hi:[1,0,0]
	v_mov_b32_e32 v0, v46
	v_mov_b32_e32 v1, v44
	v_pk_add_f32 v[0:1], v[170:171], v[0:1]
	v_lshlrev_b32_e32 v4, 16, v242
	v_and_b32_e32 v5, 0xffff0000, v242
	v_pk_fma_f32 v[0:1], v[6:7], v[4:5], v[0:1] op_sel_hi:[0,1,1] neg_lo:[1,0,0] neg_hi:[1,0,0]
	v_mov_b32_e32 v4, v47
	v_mov_b32_e32 v5, v45
	v_pk_add_f32 v[4:5], v[166:167], v[4:5]
	v_lshlrev_b32_e32 v2, 16, v243
	v_and_b32_e32 v3, 0xffff0000, v243
	v_pk_fma_f32 v[166:167], v[6:7], v[2:3], v[4:5] op_sel_hi:[0,1,1] neg_lo:[1,0,0] neg_hi:[1,0,0]
	v_mov_b32_e32 v175, v167
	v_mov_b32_e32 v171, v166
	v_mov_b32_e32 v174, v1
	v_mov_b32_e32 v170, v0
	v_mov_b32_e32 v169, v172
	v_mov_b32_e32 v172, v9
	v_mov_b32_e32 v168, v8
	s_cbranch_execnz .LBB0_437
	s_branch .LBB0_441

; __global__ void __launch_bounds__(NWAVES * 64, 2) hymba_fwd(Args args) {
;     extern __shared__ __attribute__((aligned(16))) unsigned char lds[];
	.amdhsa_kernel _Z9hymba_fwd4Args
		.amdhsa_group_segment_fixed_size 0
		.amdhsa_private_segment_fixed_size 0
		.amdhsa_kernarg_size 432
		.amdhsa_user_sgpr_count 2
		.amdhsa_user_sgpr_dispatch_ptr 0
		.amdhsa_user_sgpr_queue_ptr 0
		.amdhsa_user_sgpr_kernarg_segment_ptr 1
		.amdhsa_user_sgpr_dispatch_id 0
		.amdhsa_user_sgpr_kernarg_preload_length 0
		.amdhsa_user_sgpr_kernarg_preload_offset 0
		.amdhsa_user_sgpr_private_segment_size 0
		.amdhsa_uses_dynamic_stack 0
		.amdhsa_enable_private_segment 0
		.amdhsa_system_sgpr_workgroup_id_x 1
		.amdhsa_system_sgpr_workgroup_id_y 0
		.amdhsa_system_sgpr_workgroup_id_z 0
		.amdhsa_system_sgpr_workgroup_info 0
		.amdhsa_system_vgpr_workitem_id 2
		.amdhsa_next_free_vgpr 256
		.amdhsa_next_free_sgpr 102
		.amdhsa_accum_offset 256
		.amdhsa_reserve_vcc 1
		.amdhsa_float_round_mode_32 0
		.amdhsa_float_round_mode_16_64 0
		.amdhsa_float_denorm_mode_32 3
		.amdhsa_float_denorm_mode_16_64 3
		.amdhsa_dx10_clamp 1
		.amdhsa_ieee_mode 1
		.amdhsa_fp16_overflow 0
		.amdhsa_tg_split 0
		.amdhsa_exception_fp_ieee_invalid_op 0
		.amdhsa_exception_fp_denorm_src 0
		.amdhsa_exception_fp_ieee_div_zero 0
		.amdhsa_exception_fp_ieee_overflow 0
		.amdhsa_exception_fp_ieee_underflow 0
		.amdhsa_exception_fp_ieee_inexact 0
		.amdhsa_exception_int_div_zero 0
	.end_amdhsa_kernel

; __global__ void __launch_bounds__(NWAVES * 64, 2) hymba_fwd(Args args) {
;     extern __shared__ __attribute__((aligned(16))) unsigned char lds[];
amdhsa.kernels:
  - .agpr_count:     0
    .args:
      - .offset:         0
        .size:           176
        .value_kind:     by_value
      - .offset:         176
        .size:           4
        .value_kind:     hidden_block_count_x
      - .offset:         180
        .size:           4
        .value_kind:     hidden_block_count_y
      - .offset:         184
        .size:           4
        .value_kind:     hidden_block_count_z
      - .offset:         188
        .size:           2
        .value_kind:     hidden_group_size_x
      - .offset:         190
        .size:           2
        .value_kind:     hidden_group_size_y
      - .offset:         192
        .size:           2
        .value_kind:     hidden_group_size_z
      - .offset:         194
        .size:           2
        .value_kind:     hidden_remainder_x
      - .offset:         196
        .size:           2
        .value_kind:     hidden_remainder_y
      - .offset:         198
        .size:           2
        .value_kind:     hidden_remainder_z
      - .offset:         216
        .size:           8
        .value_kind:     hidden_global_offset_x
      - .offset:         224
        .size:           8
        .value_kind:     hidden_global_offset_y
      - .offset:         232
        .size:           8
        .value_kind:     hidden_global_offset_z
      - .offset:         240
        .size:           2
        .value_kind:     hidden_grid_dims
      - .offset:         264
        .size:           8
        .value_kind:     hidden_multigrid_sync_arg
      - .offset:         296
        .size:           4
        .value_kind:     hidden_dynamic_lds_size
    .group_segment_fixed_size: 0
    .kernarg_segment_align: 8
    .kernarg_segment_size: 432
    .language:       OpenCL C
    .language_version:
      - 2
      - 0
    .max_flat_workgroup_size: 512
    .name:           _Z9hymba_fwd4Args
    .private_segment_fixed_size: 0
    .sgpr_count:     108
    .sgpr_spill_count: 44
    .symbol:         _Z9hymba_fwd4Args.kd
    .uniform_work_group_size: 1
    .uses_dynamic_stack: false
    .vgpr_count:     256
    .vgpr_spill_count: 0
    .wavefront_size: 64
